# v10 + s5_local chunk loop: the four per-t chains renamed into free VGPRs and interleaved (all 32 MFMA first, Horner chains round-robin, batched cross-lane hops, merged carry stores)
# speedup vs baseline: 1.0098x; 1.0098x over previous
; template <int DIR>
; __device__ __forceinline__ void s5_local_dir(const bf16_t* UZ, unsigned char* ws, int gw, int NGW, int lane) {
;     ...
; #pragma unroll
;         for (int t = 0; t < 4; ++t) {
;             f32x4 cr = {0.f, 0.f, 0.f, 0.f}, ci = {0.f, 0.f, 0.f, 0.f};
; #pragma unroll
;             for (int m = 0; m < 4; ++m) {
;                 cr = __builtin_amdgcn_mfma_f32_16x16x16bf16_1k(Uf[m], Bre[m][t], cr, 0, 0, 0);
;                 ci = __builtin_amdgcn_mfma_f32_16x16x16bf16_1k(Uf[m], Bim[m][t], ci, 0, 0, 0);
;             }
;             f32x2 s2 = {DIR ? cr[3] : cr[0], DIR ? ci[3] : ci[0]};
; #pragma unroll
;             for (int ii = 1; ii < 4; ++ii) { const int i = DIR ? 3 - ii : ii;
;                 s2 = cmac(s2, (f32x2){a1r[t], a1r[t]}, (f32x2){-a1i[t], a1i[t]}, (f32x2){cr[i], ci[i]}); }
;             s2 = cmac(s2, (f32x2){wr_[t], wr_[t]}, (f32x2){-wi_[t], wi_[t]}, (f32x2){0.f, 0.f});
;             float sr = s2.x, si = s2.y;
;             sr += __shfl_xor(sr, 16); si += __shfl_xor(si, 16); sr += __shfl_xor(sr, 32); si += __shfl_xor(si, 32);
;             if (fq == 0) { e[16 * t + fr] = Rr[t]; e[64 + 16 * t + fr] = Ri[t]; }
;             const float nr = fmaf(a64r[t], Rr[t], fmaf(-a64i[t], Ri[t], sr)), ni = fmaf(a64r[t], Ri[t], fmaf(a64i[t], Rr[t], si)); Rr[t] = nr; Ri[t] = ni;
;         }
.LBB0_652:
	s_and_saveexec_b64 s[38:39], s[8:9]
	s_cbranch_execz .Lp7_d0_st
	global_store_dword v[116:117], v17, off offset:-256
	global_store_dword v[116:117], v139, off
	global_store_dword v[116:117], v137, off offset:-192
	global_store_dword v[116:117], v138, off offset:64
	global_store_dword v[116:117], v135, off offset:-128
	global_store_dword v[116:117], v136, off offset:128
	global_store_dword v[116:117], v133, off offset:-64
	global_store_dword v[116:117], v134, off offset:192
.Lp7_d0_st:
	s_or_b64 exec, exec, s[38:39]
	s_waitcnt vmcnt(15)
	v_mfma_f32_16x16x16_bf16 v[140:143], v[110:111], v[26:27], 0
	v_mfma_f32_16x16x16_bf16 v[144:147], v[110:111], v[28:29], 0
	s_waitcnt vmcnt(14)
	v_mfma_f32_16x16x16_bf16 v[140:143], v[112:113], v[30:31], v[140:143]
	v_mfma_f32_16x16x16_bf16 v[144:147], v[112:113], v[32:33], v[144:147]
	s_waitcnt vmcnt(13)
	v_mfma_f32_16x16x16_bf16 v[140:143], v[114:115], v[34:35], v[140:143]
	v_mfma_f32_16x16x16_bf16 v[144:147], v[114:115], v[36:37], v[144:147]
	s_waitcnt vmcnt(12)
	v_mfma_f32_16x16x16_bf16 v[140:143], v[108:109], v[38:39], v[140:143]
	v_mfma_f32_16x16x16_bf16 v[144:147], v[108:109], v[40:41], v[144:147]
	v_mfma_f32_16x16x16_bf16 v[196:199], v[110:111], v[48:49], 0
	v_mfma_f32_16x16x16_bf16 v[200:203], v[110:111], v[50:51], 0
	v_mfma_f32_16x16x16_bf16 v[196:199], v[112:113], v[52:53], v[196:199]
	v_mfma_f32_16x16x16_bf16 v[200:203], v[112:113], v[54:55], v[200:203]
	v_mfma_f32_16x16x16_bf16 v[196:199], v[114:115], v[56:57], v[196:199]
	v_mfma_f32_16x16x16_bf16 v[200:203], v[114:115], v[58:59], v[200:203]
	v_mfma_f32_16x16x16_bf16 v[196:199], v[108:109], v[60:61], v[196:199]
	v_mfma_f32_16x16x16_bf16 v[200:203], v[108:109], v[62:63], v[200:203]
	v_mfma_f32_16x16x16_bf16 v[208:211], v[110:111], v[70:71], 0
	v_mfma_f32_16x16x16_bf16 v[212:215], v[110:111], v[72:73], 0
	v_mfma_f32_16x16x16_bf16 v[208:211], v[112:113], v[74:75], v[208:211]
	v_mfma_f32_16x16x16_bf16 v[212:215], v[112:113], v[76:77], v[212:215]
	v_mfma_f32_16x16x16_bf16 v[208:211], v[114:115], v[78:79], v[208:211]
	v_mfma_f32_16x16x16_bf16 v[212:215], v[114:115], v[80:81], v[212:215]
	v_mfma_f32_16x16x16_bf16 v[208:211], v[108:109], v[82:83], v[208:211]
	v_mfma_f32_16x16x16_bf16 v[212:215], v[108:109], v[84:85], v[212:215]
	v_mfma_f32_16x16x16_bf16 v[228:231], v[110:111], v[92:93], 0
	v_mfma_f32_16x16x16_bf16 v[232:235], v[110:111], v[94:95], 0
	v_mfma_f32_16x16x16_bf16 v[228:231], v[112:113], v[96:97], v[228:231]
	v_mfma_f32_16x16x16_bf16 v[186:189], v[112:113], v[98:99], v[232:235]
	v_mfma_f32_16x16x16_bf16 v[228:231], v[114:115], v[100:101], v[228:231]
	v_mfma_f32_16x16x16_bf16 v[186:189], v[114:115], v[102:103], v[186:189]
	v_mfma_f32_16x16x16_bf16 v[228:231], v[108:109], v[104:105], v[228:231]
	v_mfma_f32_16x16x16_bf16 v[184:187], v[108:109], v[106:107], v[186:189]
	s_nop 6
	v_mov_b32_e32 v148, v143
	v_mov_b32_e32 v204, v199
	v_mov_b32_e32 v216, v211
	v_mov_b32_e32 v190, v231
	v_mov_b32_e32 v149, v147
	v_mov_b32_e32 v205, v203
	v_mov_b32_e32 v217, v215
	v_mov_b32_e32 v191, v187
	v_mov_b32_e32 v150, v142
	v_mov_b32_e32 v206, v198
	v_mov_b32_e32 v218, v210
	v_mov_b32_e32 v188, v230
	v_mov_b32_e32 v151, v146
	v_mov_b32_e32 v207, v202
	v_mov_b32_e32 v219, v214
	v_mov_b32_e32 v189, v186
	v_pk_fma_f32 v[148:149], v[20:21], v[148:149], v[150:151]
	v_pk_fma_f32 v[204:205], v[42:43], v[204:205], v[206:207]
	v_pk_fma_f32 v[216:217], v[64:65], v[216:217], v[218:219]
	v_pk_fma_f32 v[188:189], v[86:87], v[190:191], v[188:189]
	v_mov_b32_e32 v142, v147
	v_mov_b32_e32 v198, v203
	v_mov_b32_e32 v210, v215
	v_mov_b32_e32 v230, v187
	v_pk_fma_f32 v[142:143], v[0:1], v[142:143], v[148:149]
	v_pk_fma_f32 v[198:199], v[4:5], v[198:199], v[204:205]
	v_pk_fma_f32 v[210:211], v[8:9], v[210:211], v[216:217]
	v_pk_fma_f32 v[186:187], v[12:13], v[230:231], v[188:189]
	v_mov_b32_e32 v146, v141
	v_mov_b32_e32 v202, v197
	v_mov_b32_e32 v214, v209
	v_mov_b32_e32 v188, v229
	v_mov_b32_e32 v147, v145
	v_mov_b32_e32 v203, v201
	v_mov_b32_e32 v215, v213
	v_mov_b32_e32 v189, v185
	v_pk_fma_f32 v[146:147], v[20:21], v[142:143], v[146:147]
	v_pk_fma_f32 v[202:203], v[42:43], v[198:199], v[202:203]
	v_pk_fma_f32 v[214:215], v[64:65], v[210:211], v[214:215]
	v_pk_fma_f32 v[188:189], v[86:87], v[186:187], v[188:189]
	v_mov_b32_e32 v141, v144
	v_mov_b32_e32 v197, v200
	v_mov_b32_e32 v209, v212
	v_mov_b32_e32 v229, v184
	v_pk_fma_f32 v[142:143], v[0:1], v[142:143], v[146:147] op_sel:[0,1,0] op_sel_hi:[1,0,1]
	v_pk_fma_f32 v[198:199], v[4:5], v[198:199], v[202:203] op_sel:[0,1,0] op_sel_hi:[1,0,1]
	v_pk_fma_f32 v[210:211], v[8:9], v[210:211], v[214:215] op_sel:[0,1,0] op_sel_hi:[1,0,1]
	v_pk_fma_f32 v[186:187], v[12:13], v[186:187], v[188:189] op_sel:[0,1,0] op_sel_hi:[1,0,1]
	s_nop 0
	s_nop 0
	s_nop 0
	s_nop 0
	v_pk_fma_f32 v[140:141], v[20:21], v[142:143], v[140:141]
	v_pk_fma_f32 v[196:197], v[42:43], v[198:199], v[196:197]
	v_pk_fma_f32 v[208:209], v[64:65], v[210:211], v[208:209]
	v_pk_fma_f32 v[184:185], v[86:87], v[186:187], v[228:229]
	s_nop 0
	s_nop 0
	s_nop 0
	s_nop 0
	v_pk_fma_f32 v[140:141], v[0:1], v[142:143], v[140:141] op_sel:[0,1,0] op_sel_hi:[1,0,1]
	v_pk_fma_f32 v[196:197], v[4:5], v[198:199], v[196:197] op_sel:[0,1,0] op_sel_hi:[1,0,1]
	v_pk_fma_f32 v[208:209], v[8:9], v[210:211], v[208:209] op_sel:[0,1,0] op_sel_hi:[1,0,1]
	v_pk_fma_f32 v[184:185], v[12:13], v[186:187], v[184:185] op_sel:[0,1,0] op_sel_hi:[1,0,1]
	s_nop 0
	s_nop 0
	s_nop 0
	s_nop 0
	v_pk_fma_f32 v[142:143], v[22:23], v[140:141], 0 op_sel_hi:[1,1,0]
	v_pk_fma_f32 v[198:199], v[44:45], v[196:197], 0 op_sel_hi:[1,1,0]
	v_pk_fma_f32 v[210:211], v[66:67], v[208:209], 0 op_sel_hi:[1,1,0]
	v_pk_fma_f32 v[186:187], v[88:89], v[184:185], 0 op_sel_hi:[1,1,0]
	s_nop 0
	s_nop 0
	s_nop 0
	s_nop 0
	v_pk_fma_f32 v[140:141], v[24:25], v[140:141], v[142:143] op_sel:[0,1,0] op_sel_hi:[1,0,1]
	v_pk_fma_f32 v[196:197], v[46:47], v[196:197], v[198:199] op_sel:[0,1,0] op_sel_hi:[1,0,1]
	v_pk_fma_f32 v[208:209], v[68:69], v[208:209], v[210:211] op_sel:[0,1,0] op_sel_hi:[1,0,1]
	v_pk_fma_f32 v[184:185], v[90:91], v[184:185], v[186:187] op_sel:[0,1,0] op_sel_hi:[1,0,1]
	ds_bpermute_b32 v142, v131, v140
	ds_bpermute_b32 v143, v131, v141
	ds_bpermute_b32 v198, v131, v196
	ds_bpermute_b32 v199, v131, v197
	ds_bpermute_b32 v210, v131, v208
	ds_bpermute_b32 v211, v131, v209
	ds_bpermute_b32 v186, v131, v184
	ds_bpermute_b32 v187, v131, v185
	s_waitcnt lgkmcnt(0)
; template <int DIR>
; __device__ __forceinline__ void s5_local_dir(const bf16_t* UZ, unsigned char* ws, int gw, int NGW, int lane) {
;     ...
;             for (int ii = 1; ii < 4; ++ii) { const int i = DIR ? 3 - ii : ii;
;                 s2 = cmac(s2, (f32x2){a1r[t], a1r[t]}, (f32x2){-a1i[t], a1i[t]}, (f32x2){cr[i], ci[i]}); }
;             s2 = cmac(s2, (f32x2){wr_[t], wr_[t]}, (f32x2){-wi_[t], wi_[t]}, (f32x2){0.f, 0.f});
;             float sr = s2.x, si = s2.y;
;             sr += __shfl_xor(sr, 16); si += __shfl_xor(si, 16); sr += __shfl_xor(sr, 32); si += __shfl_xor(si, 32);
;             if (fq == 0) { e[16 * t + fr] = Rr[t]; e[64 + 16 * t + fr] = Ri[t]; }
;             const float nr = fmaf(a64r[t], Rr[t], fmaf(-a64i[t], Ri[t], sr)), ni = fmaf(a64r[t], Ri[t], fmaf(a64i[t], Rr[t], si)); Rr[t] = nr; Ri[t] = ni;
;         }
;     }
	v_add_f32_e32 v140, v140, v142
	v_add_f32_e32 v141, v141, v143
	v_add_f32_e32 v196, v196, v198
	v_add_f32_e32 v197, v197, v199
	v_add_f32_e32 v208, v208, v210
	v_add_f32_e32 v209, v209, v211
	v_add_f32_e32 v189, v184, v186
	v_add_f32_e32 v191, v185, v187
	ds_bpermute_b32 v142, v132, v140
	ds_bpermute_b32 v143, v132, v141
	ds_bpermute_b32 v198, v132, v196
	ds_bpermute_b32 v199, v132, v197
	ds_bpermute_b32 v210, v132, v208
	ds_bpermute_b32 v211, v132, v209
	ds_bpermute_b32 v228, v132, v189
	ds_bpermute_b32 v229, v132, v191
	s_waitcnt lgkmcnt(0)
	v_add_f32_e32 v109, v140, v142
	v_add_f32_e32 v108, v141, v143
	v_fma_f32 v110, -v3, v139, v109
	v_fmac_f32_e32 v110, v2, v17
	v_fmac_f32_e32 v108, v3, v17
	v_add_f32_e32 v17, v196, v198
	v_fma_f32 v112, -v7, v138, v17
	v_add_f32_e32 v17, v208, v210
	v_add_f32_e32 v109, v197, v199
	v_add_f32_e32 v111, v209, v211
	v_fma_f32 v114, -v11, v136, v17
	v_add_f32_e32 v17, v189, v228
	v_add_f32_e32 v113, v191, v229
	v_fmac_f32_e32 v109, v7, v137
	v_fmac_f32_e32 v111, v11, v135
	v_fma_f32 v115, -v15, v134, v17
	v_fmac_f32_e32 v113, v15, v133
	v_fmac_f32_e32 v108, v2, v139
	v_fmac_f32_e32 v112, v6, v137
	v_fmac_f32_e32 v109, v6, v138
	v_fmac_f32_e32 v114, v10, v135
	v_fmac_f32_e32 v111, v10, v136
	v_fmac_f32_e32 v115, v14, v133
	v_fmac_f32_e32 v113, v14, v134
	v_lshl_add_u64 v[116:117], v[116:117], 0, s[2:3]
	v_subrev_u32_e32 v16, 64, v16
	s_and_b64 vcc, exec, s[36:37]
	s_cbranch_vccnz .LBB0_684
	s_mov_b32 s38, s49
	v_mov_b32_e32 v17, v110
	v_mov_b32_e32 v137, v112
	v_mov_b32_e32 v135, v114
	v_mov_b32_e32 v133, v115
	v_mov_b32_e32 v139, v108
	v_mov_b32_e32 v138, v109
	v_mov_b32_e32 v136, v111
	v_mov_b32_e32 v134, v113
	s_waitcnt vmcnt(3)
	v_mov_b32_e32 v110, v118
	v_mov_b32_e32 v111, v119
	s_waitcnt vmcnt(2)
	v_mov_b32_e32 v112, v120
	v_mov_b32_e32 v113, v121
	s_waitcnt vmcnt(1)
	v_mov_b32_e32 v114, v122
	v_mov_b32_e32 v115, v123
	s_waitcnt vmcnt(0)
	v_mov_b32_e32 v108, v124
	v_mov_b32_e32 v109, v125
	s_branch .LBB0_649

; template <int DIR>
; __device__ __forceinline__ void s5_local_dir(const bf16_t* UZ, unsigned char* ws, int gw, int NGW, int lane) {
;     ...
; #pragma unroll
;         for (int t = 0; t < 4; ++t) {
;             f32x4 cr = {0.f, 0.f, 0.f, 0.f}, ci = {0.f, 0.f, 0.f, 0.f};
; #pragma unroll
;             for (int m = 0; m < 4; ++m) {
;                 cr = __builtin_amdgcn_mfma_f32_16x16x16bf16_1k(Uf[m], Bre[m][t], cr, 0, 0, 0);
;                 ci = __builtin_amdgcn_mfma_f32_16x16x16bf16_1k(Uf[m], Bim[m][t], ci, 0, 0, 0);
;             }
;             f32x2 s2 = {DIR ? cr[3] : cr[0], DIR ? ci[3] : ci[0]};
; #pragma unroll
;             for (int ii = 1; ii < 4; ++ii) { const int i = DIR ? 3 - ii : ii;
;                 s2 = cmac(s2, (f32x2){a1r[t], a1r[t]}, (f32x2){-a1i[t], a1i[t]}, (f32x2){cr[i], ci[i]}); }
;             s2 = cmac(s2, (f32x2){wr_[t], wr_[t]}, (f32x2){-wi_[t], wi_[t]}, (f32x2){0.f, 0.f});
;             float sr = s2.x, si = s2.y;
;             sr += __shfl_xor(sr, 16); si += __shfl_xor(si, 16); sr += __shfl_xor(sr, 32); si += __shfl_xor(si, 32);
;             if (fq == 0) { e[16 * t + fr] = Rr[t]; e[64 + 16 * t + fr] = Ri[t]; }
;             const float nr = fmaf(a64r[t], Rr[t], fmaf(-a64i[t], Ri[t], sr)), ni = fmaf(a64r[t], Ri[t], fmaf(a64i[t], Rr[t], si)); Rr[t] = nr; Ri[t] = ni;
;         }
.LBB0_674:
	s_and_saveexec_b64 s[24:25], s[2:3]
	s_cbranch_execz .Lp7_d1_st
	global_store_dword v[116:117], v21, off offset:-256
	global_store_dword v[116:117], v135, off
	global_store_dword v[116:117], v133, off offset:-192
	global_store_dword v[116:117], v134, off offset:64
	global_store_dword v[116:117], v131, off offset:-128
	global_store_dword v[116:117], v132, off offset:128
	global_store_dword v[116:117], v127, off offset:-64
	global_store_dword v[116:117], v130, off offset:192
.Lp7_d1_st:
	s_or_b64 exec, exec, s[24:25]
	s_waitcnt vmcnt(15)
	v_mfma_f32_16x16x16_bf16 v[136:139], v[108:109], v[26:27], 0
	v_mfma_f32_16x16x16_bf16 v[140:143], v[108:109], v[28:29], 0
	s_waitcnt vmcnt(14)
	v_mfma_f32_16x16x16_bf16 v[136:139], v[112:113], v[30:31], v[136:139]
	v_mfma_f32_16x16x16_bf16 v[140:143], v[112:113], v[32:33], v[140:143]
	s_waitcnt vmcnt(13)
	v_mfma_f32_16x16x16_bf16 v[136:139], v[114:115], v[34:35], v[136:139]
	v_mfma_f32_16x16x16_bf16 v[140:143], v[114:115], v[36:37], v[140:143]
	s_waitcnt vmcnt(12)
	v_mfma_f32_16x16x16_bf16 v[136:139], v[110:111], v[38:39], v[136:139]
	v_mfma_f32_16x16x16_bf16 v[140:143], v[110:111], v[40:41], v[140:143]
	v_mfma_f32_16x16x16_bf16 v[196:199], v[108:109], v[48:49], 0
	v_mfma_f32_16x16x16_bf16 v[200:203], v[108:109], v[50:51], 0
	v_mfma_f32_16x16x16_bf16 v[196:199], v[112:113], v[52:53], v[196:199]
	v_mfma_f32_16x16x16_bf16 v[200:203], v[112:113], v[54:55], v[200:203]
	v_mfma_f32_16x16x16_bf16 v[196:199], v[114:115], v[56:57], v[196:199]
	v_mfma_f32_16x16x16_bf16 v[200:203], v[114:115], v[58:59], v[200:203]
	v_mfma_f32_16x16x16_bf16 v[196:199], v[110:111], v[60:61], v[196:199]
	v_mfma_f32_16x16x16_bf16 v[200:203], v[110:111], v[62:63], v[200:203]
	v_mfma_f32_16x16x16_bf16 v[208:211], v[108:109], v[70:71], 0
	v_mfma_f32_16x16x16_bf16 v[212:215], v[108:109], v[72:73], 0
	v_mfma_f32_16x16x16_bf16 v[208:211], v[112:113], v[74:75], v[208:211]
	v_mfma_f32_16x16x16_bf16 v[212:215], v[112:113], v[76:77], v[212:215]
	v_mfma_f32_16x16x16_bf16 v[208:211], v[114:115], v[78:79], v[208:211]
	v_mfma_f32_16x16x16_bf16 v[212:215], v[114:115], v[80:81], v[212:215]
	v_mfma_f32_16x16x16_bf16 v[208:211], v[110:111], v[82:83], v[208:211]
	v_mfma_f32_16x16x16_bf16 v[212:215], v[110:111], v[84:85], v[212:215]
	v_mfma_f32_16x16x16_bf16 v[224:227], v[108:109], v[88:89], 0
	v_mfma_f32_16x16x16_bf16 v[228:231], v[108:109], v[90:91], 0
	v_mfma_f32_16x16x16_bf16 v[224:227], v[112:113], v[96:97], v[224:227]
	v_mfma_f32_16x16x16_bf16 v[228:231], v[112:113], v[98:99], v[228:231]
	v_mfma_f32_16x16x16_bf16 v[224:227], v[114:115], v[100:101], v[224:227]
	v_mfma_f32_16x16x16_bf16 v[188:191], v[114:115], v[102:103], v[228:231]
	v_mfma_f32_16x16x16_bf16 v[224:227], v[110:111], v[104:105], v[224:227]
	v_mfma_f32_16x16x16_bf16 v[184:187], v[110:111], v[106:107], v[188:191]
	s_nop 6
	v_mov_b32_e32 v144, v136
	v_mov_b32_e32 v204, v196
	v_mov_b32_e32 v216, v208
	v_mov_b32_e32 v228, v224
	v_mov_b32_e32 v145, v140
	v_mov_b32_e32 v205, v200
	v_mov_b32_e32 v217, v212
	v_mov_b32_e32 v229, v184
	v_mov_b32_e32 v146, v137
	v_mov_b32_e32 v206, v197
	v_mov_b32_e32 v218, v209
	v_mov_b32_e32 v188, v225
	v_mov_b32_e32 v147, v141
	v_mov_b32_e32 v207, v201
	v_mov_b32_e32 v219, v213
	v_mov_b32_e32 v189, v185
	v_pk_fma_f32 v[144:145], v[18:19], v[144:145], v[146:147]
	v_pk_fma_f32 v[204:205], v[42:43], v[204:205], v[206:207]
	v_pk_fma_f32 v[216:217], v[64:65], v[216:217], v[218:219]
	v_pk_fma_f32 v[188:189], v[86:87], v[228:229], v[188:189]
	v_mov_b32_e32 v141, v136
	v_mov_b32_e32 v201, v196
	v_mov_b32_e32 v213, v208
	v_mov_b32_e32 v185, v224
	v_pk_fma_f32 v[136:137], v[0:1], v[140:141], v[144:145]
	v_pk_fma_f32 v[196:197], v[4:5], v[200:201], v[204:205]
	v_pk_fma_f32 v[208:209], v[8:9], v[212:213], v[216:217]
	v_pk_fma_f32 v[184:185], v[12:13], v[184:185], v[188:189]
	v_mov_b32_e32 v140, v138
	v_mov_b32_e32 v200, v198
	v_mov_b32_e32 v212, v210
	v_mov_b32_e32 v188, v226
	v_mov_b32_e32 v141, v142
	v_mov_b32_e32 v201, v202
	v_mov_b32_e32 v213, v214
	v_mov_b32_e32 v189, v186
	v_pk_fma_f32 v[140:141], v[18:19], v[136:137], v[140:141]
	v_pk_fma_f32 v[200:201], v[42:43], v[196:197], v[200:201]
	v_pk_fma_f32 v[212:213], v[64:65], v[208:209], v[212:213]
	v_pk_fma_f32 v[188:189], v[86:87], v[184:185], v[188:189]
	v_mov_b32_e32 v142, v139
	v_mov_b32_e32 v202, v199
	v_mov_b32_e32 v214, v211
	v_mov_b32_e32 v186, v227
	v_pk_fma_f32 v[136:137], v[0:1], v[136:137], v[140:141] op_sel:[0,1,0] op_sel_hi:[1,0,1]
	v_pk_fma_f32 v[196:197], v[4:5], v[196:197], v[200:201] op_sel:[0,1,0] op_sel_hi:[1,0,1]
	v_pk_fma_f32 v[208:209], v[8:9], v[208:209], v[212:213] op_sel:[0,1,0] op_sel_hi:[1,0,1]
	v_pk_fma_f32 v[184:185], v[12:13], v[184:185], v[188:189] op_sel:[0,1,0] op_sel_hi:[1,0,1]
	s_nop 0
	s_nop 0
	s_nop 0
	s_nop 0
	v_pk_fma_f32 v[138:139], v[18:19], v[136:137], v[142:143]
	v_pk_fma_f32 v[198:199], v[42:43], v[196:197], v[202:203]
	v_pk_fma_f32 v[210:211], v[64:65], v[208:209], v[214:215]
	v_pk_fma_f32 v[186:187], v[86:87], v[184:185], v[186:187]
	s_nop 0
	s_nop 0
	s_nop 0
	s_nop 0
	v_pk_fma_f32 v[136:137], v[0:1], v[136:137], v[138:139] op_sel:[0,1,0] op_sel_hi:[1,0,1]
	v_pk_fma_f32 v[196:197], v[4:5], v[196:197], v[198:199] op_sel:[0,1,0] op_sel_hi:[1,0,1]
	v_pk_fma_f32 v[208:209], v[8:9], v[208:209], v[210:211] op_sel:[0,1,0] op_sel_hi:[1,0,1]
	v_pk_fma_f32 v[184:185], v[12:13], v[184:185], v[186:187] op_sel:[0,1,0] op_sel_hi:[1,0,1]
	s_nop 0
	s_nop 0
	s_nop 0
	s_nop 0
	v_pk_fma_f32 v[138:139], v[22:23], v[136:137], 0 op_sel_hi:[1,1,0]
	v_pk_fma_f32 v[198:199], v[44:45], v[196:197], 0 op_sel_hi:[1,1,0]
	v_pk_fma_f32 v[210:211], v[66:67], v[208:209], 0 op_sel_hi:[1,1,0]
	v_pk_fma_f32 v[186:187], v[92:93], v[184:185], 0 op_sel_hi:[1,1,0]
	s_nop 0
	s_nop 0
	s_nop 0
	s_nop 0
	v_pk_fma_f32 v[136:137], v[24:25], v[136:137], v[138:139] op_sel:[0,1,0] op_sel_hi:[1,0,1]
	v_pk_fma_f32 v[196:197], v[46:47], v[196:197], v[198:199] op_sel:[0,1,0] op_sel_hi:[1,0,1]
	v_pk_fma_f32 v[208:209], v[68:69], v[208:209], v[210:211] op_sel:[0,1,0] op_sel_hi:[1,0,1]
	v_pk_fma_f32 v[184:185], v[94:95], v[184:185], v[186:187] op_sel:[0,1,0] op_sel_hi:[1,0,1]
	ds_bpermute_b32 v138, v128, v136
	ds_bpermute_b32 v139, v128, v137
	ds_bpermute_b32 v198, v128, v196
	ds_bpermute_b32 v199, v128, v197
	ds_bpermute_b32 v210, v128, v208
	ds_bpermute_b32 v211, v128, v209
	ds_bpermute_b32 v186, v128, v184
	ds_bpermute_b32 v187, v128, v185
	s_waitcnt lgkmcnt(0)
; template <int DIR>
; __device__ __forceinline__ void s5_local_dir(const bf16_t* UZ, unsigned char* ws, int gw, int NGW, int lane) {
;     ...
;             for (int ii = 1; ii < 4; ++ii) { const int i = DIR ? 3 - ii : ii;
;                 s2 = cmac(s2, (f32x2){a1r[t], a1r[t]}, (f32x2){-a1i[t], a1i[t]}, (f32x2){cr[i], ci[i]}); }
;             s2 = cmac(s2, (f32x2){wr_[t], wr_[t]}, (f32x2){-wi_[t], wi_[t]}, (f32x2){0.f, 0.f});
;             float sr = s2.x, si = s2.y;
;             sr += __shfl_xor(sr, 16); si += __shfl_xor(si, 16); sr += __shfl_xor(sr, 32); si += __shfl_xor(si, 32);
;             if (fq == 0) { e[16 * t + fr] = Rr[t]; e[64 + 16 * t + fr] = Ri[t]; }
;             const float nr = fmaf(a64r[t], Rr[t], fmaf(-a64i[t], Ri[t], sr)), ni = fmaf(a64r[t], Ri[t], fmaf(a64i[t], Rr[t], si)); Rr[t] = nr; Ri[t] = ni;
;         }
;     }
	v_add_f32_e32 v136, v136, v138
	v_add_f32_e32 v137, v137, v139
	v_add_f32_e32 v196, v196, v198
	v_add_f32_e32 v197, v197, v199
	v_add_f32_e32 v208, v208, v210
	v_add_f32_e32 v209, v209, v211
	v_add_f32_e32 v189, v184, v186
	v_add_f32_e32 v191, v185, v187
	ds_bpermute_b32 v138, v129, v136
	ds_bpermute_b32 v139, v129, v137
	ds_bpermute_b32 v198, v129, v196
	ds_bpermute_b32 v199, v129, v197
	ds_bpermute_b32 v210, v129, v208
	ds_bpermute_b32 v211, v129, v209
	ds_bpermute_b32 v224, v129, v189
	ds_bpermute_b32 v225, v129, v191
	s_waitcnt lgkmcnt(0)
	v_add_f32_e32 v109, v136, v138
	v_add_f32_e32 v108, v137, v139
	v_fma_f32 v110, -v3, v135, v109
	v_fmac_f32_e32 v110, v2, v21
	v_fmac_f32_e32 v108, v3, v21
	v_add_f32_e32 v21, v196, v198
	v_fma_f32 v112, -v7, v134, v21
	v_add_f32_e32 v21, v208, v210
	v_add_f32_e32 v109, v197, v199
	v_add_f32_e32 v111, v209, v211
	v_fma_f32 v114, -v11, v132, v21
	v_add_f32_e32 v21, v189, v224
	v_add_f32_e32 v113, v191, v225
	v_fmac_f32_e32 v109, v7, v133
	v_fmac_f32_e32 v111, v11, v131
	v_fma_f32 v115, -v15, v130, v21
	v_fmac_f32_e32 v113, v15, v127
	v_fmac_f32_e32 v108, v2, v135
	v_fmac_f32_e32 v112, v6, v133
	v_fmac_f32_e32 v109, v6, v134
	v_fmac_f32_e32 v114, v10, v131
	v_fmac_f32_e32 v111, v10, v132
	v_fmac_f32_e32 v115, v14, v127
	v_fmac_f32_e32 v113, v14, v130
	v_lshl_add_u64 v[116:117], v[116:117], 0, s[4:5]
	v_add_u32_e32 v20, 64, v20
	s_and_b64 vcc, exec, s[22:23]
	s_cbranch_vccnz .LBB0_702
	s_mov_b32 s24, s40
	v_mov_b32_e32 v21, v110
	v_mov_b32_e32 v133, v112
	v_mov_b32_e32 v131, v114
	v_mov_b32_e32 v127, v115
	v_mov_b32_e32 v135, v108
	v_mov_b32_e32 v134, v109
	v_mov_b32_e32 v132, v111
	v_mov_b32_e32 v130, v113
	s_waitcnt vmcnt(3)
	v_mov_b32_e32 v108, v118
	v_mov_b32_e32 v109, v119
	s_waitcnt vmcnt(2)
	v_mov_b32_e32 v112, v120
	v_mov_b32_e32 v113, v121
	s_waitcnt vmcnt(1)
	v_mov_b32_e32 v114, v122
	v_mov_b32_e32 v115, v123
	s_waitcnt vmcnt(0)
	v_mov_b32_e32 v110, v124
	v_mov_b32_e32 v111, v125
	s_branch .LBB0_671
